# first two x rows of phase 1 requested inside the barrier-1 wait window
# baseline (speedup 1.0000x reference)
.LBB0_115:
	s_waitcnt vmcnt(4)
	ds_write_b32 v110, v100
	ds_write_b32 v110, v101 offset:264
	ds_write_b32 v110, v102 offset:528
	ds_write_b32 v110, v103 offset:792
	ds_write_b32 v110, v104 offset:1056
	ds_write_b32 v110, v105 offset:1320
	ds_write_b32 v110, v106 offset:1584
	ds_write_b32 v110, v107 offset:1848
	s_waitcnt lgkmcnt(0)
	ds_read_b32 v112, v111
	ds_read_b32 v113, v111 offset:132
	ds_read_b32 v114, v111 offset:264
	ds_read_b32 v115, v111 offset:396
	ds_read_b32 v116, v111 offset:528
	ds_read_b32 v117, v111 offset:660
	ds_read_b32 v118, v111 offset:792
	ds_read_b32 v119, v111 offset:924
	s_waitcnt lgkmcnt(0)
	v_cvt_pk_bf16_f32 v120, v112, v113
	v_cvt_pk_bf16_f32 v121, v114, v115
	v_cvt_pk_bf16_f32 v122, v116, v117
	v_cvt_pk_bf16_f32 v123, v118, v119
	s_add_u32 s100, s82, 0x900000
	s_addc_u32 s101, s83, 0
	global_store_dwordx4 v124, v[120:123], s[100:101]
	v_mov_b32_e32 v2, v12
	v_readlane_b32 s2, v253, 0
	v_readlane_b32 s3, v253, 1
	v_and_b32_e32 v208, 63, v0
	v_lshlrev_b32_e32 v200, 4, v208
	v_readfirstlane_b32 s0, v0
	s_ashr_i32 s28, s0, 6
	s_lshl_b32 s29, s64, 3
	s_add_i32 s0, s28, s29
	s_mov_b32 s1, 0
	s_lshl_b64 s[22:23], s[0:1], 12
	s_add_u32 s22, s44, s22
	s_addc_u32 s23, s45, s23
	global_load_dwordx4 v[6:9], v200, s[22:23] nt
	global_load_dwordx4 v[2:5], v200, s[22:23] offset:1024 nt
	global_load_dwordx4 v[14:17], v200, s[22:23] offset:2048 nt
	global_load_dwordx4 v[10:13], v200, s[22:23] offset:3072 nt
	s_add_i32 s24, s0, 0x800
	s_mov_b32 s25, 0
	s_lshl_b64 s[24:25], s[24:25], 12
	s_add_u32 s24, s44, s24
	s_addc_u32 s25, s45, s25
	global_load_dwordx4 v[22:25], v200, s[24:25] nt
	global_load_dwordx4 v[18:21], v200, s[24:25] offset:1024 nt
	global_load_dwordx4 v[30:33], v200, s[24:25] offset:2048 nt
	global_load_dwordx4 v[26:29], v200, s[24:25] offset:3072 nt
	s_mov_b64 s[20:21], exec
	v_readlane_b32 s22, v254, 6
	s_nop 3
	s_mov_b32 exec_lo, s22
	s_mov_b32 exec_hi, 0
	s_cbranch_execz .Lsplit1_join
	v_mov_b32_e32 v240, 0x7000
	v_mov_b32_e32 v242, 0

.Lsplit1_join:
	s_mov_b64 exec, s[20:21]
	v_mov_b32_e32 v209, v0
	s_waitcnt lgkmcnt(0)
	s_barrier
	s_lshl_b32 s29, s64, 3
	v_readfirstlane_b32 s0, v209
	s_ashr_i32 s28, s0, 6
	s_add_i32 s0, s28, s29
	s_cmpk_lt_i32 s0, 0x4000
	v_and_b32_e32 v208, 63, v209
	s_cselect_b64 s[4:5], -1, 0
	s_and_b64 vcc, exec, s[4:5]
	v_lshlrev_b32_e32 v200, 4, v208
	s_cbranch_vccz .LBB0_66
	s_ashr_i32 s1, s0, 31
	s_lshl_b64 s[8:9], s[0:1], 12
	s_add_u32 s8, s44, s8
	s_addc_u32 s9, s45, s9
.LBB0_66:
	v_readlane_b32 s1, v254, 2
	s_lshl_b32 s1, s1, 3
	s_add_i32 s8, s0, s1
	s_cmpk_gt_i32 s8, 0x3fff
	s_cbranch_scc1 .LBB0_68
	s_ashr_i32 s9, s8, 31
	s_lshl_b64 s[8:9], s[8:9], 12
	s_add_u32 s8, s44, s8
	s_addc_u32 s9, s45, s9
.LBB0_68:
	s_movk_i32 s7, 0xff
	v_lshlrev_b32_e32 v34, 2, v209
	v_cmp_lt_i32_e32 vcc, s7, v209
	v_ashrrev_i32_e32 v35, 31, v34
	v_lshl_add_u32 v1, v34, 2, 0
	s_and_saveexec_b64 s[8:9], vcc
	s_xor_b64 s[8:9], exec, s[8:9]
	s_cbranch_execz .LBB0_70
	s_add_u32 s10, s82, 0xb00000
	s_addc_u32 s11, s83, 0
	v_add_u32_e32 v36, 0xfffffc00, v34
	v_add_u32_e32 v44, 0x400, v34
	v_add_u32_e32 v46, 0x800, v34
	v_add_u32_e32 v52, 0xc00, v34
	v_add_u32_e32 v54, 0x1000, v34
	v_add_u32_e32 v60, 0x1400, v34
	v_ashrrev_i32_e32 v37, 31, v36
	v_lshl_add_u64 v[40:41], v[34:35], 2, s[10:11]
	v_ashrrev_i32_e32 v45, 31, v44
	v_ashrrev_i32_e32 v47, 31, v46
	v_ashrrev_i32_e32 v53, 31, v52
	v_ashrrev_i32_e32 v55, 31, v54
	v_ashrrev_i32_e32 v61, 31, v60
	v_add_u32_e32 v34, 0x1800, v34
	v_lshl_add_u64 v[36:37], v[36:37], 2, s[10:11]
	v_lshl_add_u64 v[44:45], v[44:45], 2, s[10:11]
	v_lshl_add_u64 v[48:49], v[46:47], 2, s[10:11]
	v_lshl_add_u64 v[52:53], v[52:53], 2, s[10:11]
	v_lshl_add_u64 v[56:57], v[54:55], 2, s[10:11]
	v_lshl_add_u64 v[60:61], v[60:61], 2, s[10:11]
	v_ashrrev_i32_e32 v35, 31, v34
	global_load_dwordx4 v[36:39], v[36:37], off
	s_nop 0
	global_load_dwordx4 v[40:43], v[40:41], off
	s_nop 0
	global_load_dwordx4 v[44:47], v[44:45], off
	s_nop 0
	global_load_dwordx4 v[48:51], v[48:49], off
	s_nop 0
	global_load_dwordx4 v[52:55], v[52:53], off
	s_nop 0
	global_load_dwordx4 v[56:59], v[56:57], off
	v_lshl_add_u64 v[34:35], v[34:35], 2, s[10:11]
	global_load_dwordx4 v[60:63], v[60:61], off
	s_nop 0
	global_load_dwordx4 v[64:67], v[34:35], off
	s_waitcnt vmcnt(7)
	ds_write_b128 v1, v[36:39] offset:4096
	s_waitcnt vmcnt(6)
	ds_write_b128 v1, v[40:43] offset:8192
	s_waitcnt vmcnt(5)
	ds_write_b128 v1, v[44:47] offset:12288
	s_waitcnt vmcnt(4)
	ds_write_b128 v1, v[48:51] offset:16384
	s_waitcnt vmcnt(3)
	ds_write_b128 v1, v[52:55] offset:20480
	s_waitcnt vmcnt(2)
	ds_write_b128 v1, v[56:59] offset:24576
	s_waitcnt vmcnt(1)
	ds_write_b128 v1, v[60:63] offset:28672
	s_waitcnt vmcnt(0)
	ds_write_b128 v1, v[64:67] offset:32768
